# mixer: rpb bias table loaded to LDS once per phase per workgroup instead of per item
# baseline (speedup 1.0000x reference)
; #define LAS __attribute__((address_space(3)))
; __device__ __forceinline__ int kswz(int key) { return ((key >> 1) & 1) | (((key >> 3) & 3) << 1); }
; __device__ __forceinline__ void phase_mixer(const Params& p, LAS unsigned char* lds, int l, bool with_ctx, int G, int tid, int wave, int lane, int rep_attn, int rep_pool) {
;     ...
;         {
;             const int tok0 = b * SEQ + rs0 * 64;
;             const bf16_t* ksrc = PB + (size_t)(tok0 + (tid >> 3)) * PBW + 1024 + h * 64 + (tid & 7) * 8;
;             u32x4 kreg[9], vreg[9];
; #pragma unroll
;             for (int ps = 0; ps < 9; ++ps) { const int idx = ps * 512 + tid, d = idx / 72, ch = idx - d * 72;
;                 kreg[ps] = *(const u32x4*)(ksrc + (size_t)(ps * 64) * PBW);
;                 vreg[ps] = *(const u32x4*)(VT + (size_t)(h * 64 + d) * VTP + tok0 + ch * 8); }
;             __builtin_amdgcn_sched_barrier(0);
; #pragma unroll
;             for (int ps = 0; ps < 9; ++ps) { const int key = ps * 64 + (tid >> 3), idx = ps * 512 + tid, d = idx / 72, ch = idx - d * 72;
;                 *(LAS u32x4*)(lds + AT_KL + key * 128 + ((((tid & 7) ^ kswz(key))) << 4)) = kreg[ps];
;                 *(LAS u32x4*)(lds + AT_VL + d * AT_VLP + ((ch ^ (d & 15)) << 4)) = vreg[ps]; }
;             LAS float* rp = (LAS float*)(lds + AT_RPB);
;             for (int i = tid; i < 15 * RPB_PITCH; i += NTHR) { const int row = i >> 6, cc = (i & 63) - RPB_OFF; rp[i] = (cc >= 0 && cc < 31) ? p.in[I_RPB][(size_t)(l * 8 + h) * 15 * 31 + row * 31 + cc] * LOG2E : 0.f; }
;         }
.LBB0_301:
	v_sub_u32_e64 v24, s71, 4 clamp
	v_min_u32_e32 v26, 56, v24
	v_lshlrev_b32_e32 v24, 6, v26
	v_or_b32_e32 v24, s76, v24
	v_add_u32_e32 v25, v24, v109
	v_mov_b64_e32 v[30:31], s[0:1]
	v_mad_i64_i32 v[30:31], s[68:69], v25, s58, v[30:31]
	v_ashrrev_i32_e32 v25, 31, v24
	s_lshl_b32 s30, s70, 1
	v_lshlrev_b64 v[24:25], 1, v[24:25]
	v_lshl_add_u64 v[30:31], v[30:31], 0, s[30:31]
	v_lshl_add_u64 v[24:25], s[28:29], 0, v[24:25]
	v_add_u32_e32 v27, s70, v116
	s_mov_b32 s71, 0x11100
	v_lshl_add_u64 v[70:71], v[30:31], 0, v[156:157]
	v_mad_i64_i32 v[30:31], s[68:69], v27, s71, v[24:25]
	s_mov_b32 s68, 0x30000
	v_add_u32_e32 v27, s70, v117
	v_add_co_u32_e32 v38, vcc, s68, v70
	v_mad_i64_i32 v[40:41], s[68:69], v27, s71, v[24:25]
	s_nop 0
	v_addc_co_u32_e32 v39, vcc, 0, v71, vcc
	s_mov_b32 s68, 0x60000
	v_add_u32_e32 v27, s70, v118
	v_add_co_u32_e32 v46, vcc, s68, v70
	v_mad_i64_i32 v[48:49], s[68:69], v27, s71, v[24:25]
	s_nop 0
	v_addc_co_u32_e32 v47, vcc, 0, v71, vcc
	s_mov_b32 s68, 0x90000
	v_add_u32_e32 v27, s70, v119
	v_add_co_u32_e32 v54, vcc, s68, v70
	v_mad_i64_i32 v[56:57], s[68:69], v27, s71, v[24:25]
	s_nop 0
	v_addc_co_u32_e32 v55, vcc, 0, v71, vcc
	s_mov_b32 s68, 0xc0000
	v_add_u32_e32 v27, s70, v120
	v_add_co_u32_e32 v62, vcc, s68, v70
	v_mad_i64_i32 v[64:65], s[68:69], v27, s71, v[24:25]
	s_nop 0
	v_addc_co_u32_e32 v63, vcc, 0, v71, vcc
	s_mov_b32 s68, 0xf0000
	v_add_u32_e32 v27, s70, v121
	v_add_co_u32_e32 v100, vcc, s68, v70
	v_mad_i64_i32 v[102:103], s[68:69], v27, s71, v[24:25]
	v_lshl_add_u64 v[34:35], v[72:73], 1, v[30:31]
	v_lshl_add_u64 v[42:43], v[74:75], 1, v[40:41]
	v_lshl_add_u64 v[50:51], v[76:77], 1, v[48:49]
	v_lshl_add_u64 v[58:59], v[78:79], 1, v[56:57]
	v_lshl_add_u64 v[66:67], v[80:81], 1, v[64:65]
	v_addc_co_u32_e32 v101, vcc, 0, v71, vcc
	v_lshl_add_u64 v[104:105], v[82:83], 1, v[102:103]
	s_mov_b32 s68, 0x120000
	v_add_u32_e32 v27, s70, v122
	s_barrier
	global_load_dwordx4 v[30:33], v[70:71], off offset:2048
	s_nop 0
	global_load_dwordx4 v[34:37], v[34:35], off
	s_nop 0
	global_load_dwordx4 v[38:41], v[38:39], off offset:2048
	s_nop 0
	global_load_dwordx4 v[42:45], v[42:43], off
	s_nop 0
	global_load_dwordx4 v[46:49], v[46:47], off offset:2048
	s_nop 0
	global_load_dwordx4 v[50:53], v[50:51], off
	s_nop 0
	global_load_dwordx4 v[54:57], v[54:55], off offset:2048
	s_nop 0
	global_load_dwordx4 v[58:61], v[58:59], off
	s_nop 0
	global_load_dwordx4 v[62:65], v[62:63], off offset:2048
	s_nop 0
	global_load_dwordx4 v[66:69], v[66:67], off
	s_nop 0
	global_load_dwordx4 v[100:103], v[100:101], off offset:2048
	s_nop 0
	global_load_dwordx4 v[152:155], v[104:105], off
	v_add_co_u32_e32 v104, vcc, s68, v70
	v_mad_i64_i32 v[170:171], s[68:69], v27, s71, v[24:25]
	s_nop 0
	v_addc_co_u32_e32 v105, vcc, 0, v71, vcc
	v_lshl_add_u64 v[174:175], v[84:85], 1, v[170:171]
	s_mov_b32 s68, 0x150000
	v_add_u32_e32 v27, s70, v123
	global_load_dwordx4 v[170:173], v[104:105], off offset:2048
	s_nop 0
	global_load_dwordx4 v[174:177], v[174:175], off
	v_add_co_u32_e32 v104, vcc, s68, v70
	v_mad_i64_i32 v[178:179], s[68:69], v27, s71, v[24:25]
	s_nop 0
	v_addc_co_u32_e32 v105, vcc, 0, v71, vcc
	s_mov_b32 s68, 0x180000
	v_add_co_u32_e32 v70, vcc, s68, v70
	v_add_u32_e32 v27, s70, v124
	v_lshl_add_u64 v[182:183], v[86:87], 1, v[178:179]
	v_addc_co_u32_e32 v71, vcc, 0, v71, vcc
	v_mad_i64_i32 v[24:25], s[68:69], v27, s71, v[24:25]
	global_load_dwordx4 v[178:181], v[104:105], off offset:2048
	s_nop 0
	global_load_dwordx4 v[182:185], v[182:183], off
	v_lshl_add_u64 v[24:25], v[88:89], 1, v[24:25]
	global_load_dwordx4 v[186:189], v[70:71], off offset:2048
	global_load_dwordx4 v[190:193], v[24:25], off
	s_waitcnt vmcnt(17)
	ds_write_b128 v111, v[30:33]
	s_waitcnt vmcnt(16)
	ds_write_b128 v142, v[34:37]
	s_waitcnt vmcnt(15)
	ds_write_b128 v111, v[38:41] offset:8192
	s_waitcnt vmcnt(14)
	ds_write_b128 v143, v[42:45]
	s_waitcnt vmcnt(13)
	ds_write_b128 v111, v[46:49] offset:16384
	s_waitcnt vmcnt(12)
	ds_write_b128 v144, v[50:53]
	s_waitcnt vmcnt(11)
	ds_write_b128 v111, v[54:57] offset:24576
	s_waitcnt vmcnt(10)
	ds_write_b128 v145, v[58:61]
	s_waitcnt vmcnt(9)
	ds_write_b128 v111, v[62:65] offset:32768
	s_waitcnt vmcnt(8)
	ds_write_b128 v146, v[66:69]
	s_waitcnt vmcnt(7)
	ds_write_b128 v111, v[100:103] offset:40960
	s_waitcnt vmcnt(6)
	ds_write_b128 v147, v[152:155]
	s_waitcnt vmcnt(5)
	ds_write_b128 v111, v[170:173] offset:49152
	s_waitcnt vmcnt(4)
	ds_write_b128 v148, v[174:177]
	s_waitcnt vmcnt(3)
	ds_write_b128 v111, v[178:181] offset:57344
	s_waitcnt vmcnt(2)
	ds_write_b128 v149, v[182:185]
	s_waitcnt vmcnt(1)
	ds_write_b128 v125, v[186:189]
	s_waitcnt vmcnt(0)
	ds_write_b128 v150, v[190:193]
	s_mov_b32 s80, 0x3a800000
	s_mov_b64 s[68:69], exec
	s_cmp_eq_u32 s61, s2
	s_cbranch_scc1 .Lrpb_load
	s_and_b32 s32, s3, 7
	s_cmp_eq_u32 s32, 0
	s_cbranch_scc1 .LBB0_296
.Lrpb_load:
	s_and_saveexec_b64 s[68:69], s[4:5]
	s_cbranch_execz .LBB0_296
	s_or_b32 s65, s65, s53
	v_mov_b32_e32 v24, 0x744
	v_mad_i64_i32 v[24:25], s[70:71], s65, v24, v[90:91]
	s_mov_b64 s[70:71], 0
	v_mov_b32_e32 v27, v130
	v_mov_b32_e32 v29, v166
	s_branch .LBB0_304
